# P0 weight-transpose jobs hand-written (next-tile prefetch, double-buffered LDS tile) + 6-slot pipelined K-loop for P5 small tiles
# baseline (speedup 1.0000x reference)
.LBB0_19:
	s_load_dwordx16 s[76:91], s[0:1], 0x80
	s_load_dwordx4 s[28:31], s[0:1], 0x110
	s_waitcnt lgkmcnt(0)
	s_cmp_gt_i32 s28, 0
	s_cselect_b64 s[4:5], -1, 0
	s_cmp_lt_i32 s29, 1
	s_cselect_b64 s[6:7], -1, 0
	s_or_b64 s[4:5], s[4:5], s[6:7]
	s_and_b64 vcc, exec, s[4:5]
	s_cbranch_vccnz .LBB0_123
	s_cmpk_gt_i32 s2, 0x35e1
	s_cbranch_scc1 .LBB0_78
	s_load_dwordx2 s[30:31], s[0:1], 0x40
	s_load_dwordx2 s[32:33], s[0:1], 0xb0
	s_load_dwordx2 s[34:35], s[0:1], 0xc8
	s_load_dwordx2 s[36:37], s[0:1], 0xd0
	s_load_dwordx2 s[38:39], s[0:1], 0xe0
	s_load_dword s3, s[0:1], 0x120
	v_lshrrev_b32_e32 v0, 4, v204
	v_and_b32_e32 v1, 15, v204
	v_lshlrev_b32_e32 v1, 4, v1
	v_lshrrev_b32_e32 v2, 3, v204
	v_and_b32_e32 v3, 7, v204
	v_add_u32_e32 v8, 0, v0
	v_mul_u32_u24_e32 v8, 0x104, v8
	v_add3_u32 v8, v8, v1, 32
	v_add_u32_e32 v72, 0x4100, v8
	v_add_u32_e32 v9, 16, v0
	v_mul_u32_u24_e32 v9, 0x104, v9
	v_add3_u32 v9, v9, v1, 32
	v_add_u32_e32 v73, 0x4100, v9
	v_add_u32_e32 v10, 32, v0
	v_mul_u32_u24_e32 v10, 0x104, v10
	v_add3_u32 v10, v10, v1, 32
	v_add_u32_e32 v74, 0x4100, v10
	v_add_u32_e32 v11, 48, v0
	v_mul_u32_u24_e32 v11, 0x104, v11
	v_add3_u32 v11, v11, v1, 32
	v_add_u32_e32 v75, 0x4100, v11
	v_mul_u32_u24_e32 v12, 0x820, v3
	v_lshl_add_u32 v12, v2, 2, v12
	v_add_u32_e32 v12, 32, v12
	v_add_u32_e32 v13, 0x410, v12
	v_add_u32_e32 v76, 0x4100, v12
	v_add_u32_e32 v77, 0x4100, v13
	v_lshlrev_b32_e32 v14, 12, v2
	v_lshl_add_u32 v14, v3, 4, v14
	v_add_u32_e32 v15, 0x20000, v14
	v_add_u32_e32 v78, 0, v0
	v_add_u32_e32 v79, 16, v0
	v_add_u32_e32 v80, 32, v0
	v_add_u32_e32 v81, 48, v0
	s_waitcnt lgkmcnt(0)
	s_mov_b32 s4, s2
.Ltr_j0:
	s_cmpk_ge_i32 s4, 0x980
	s_cbranch_scc1 .Ltr_j0d
	s_add_u32 s4, s4, s3
	s_branch .Ltr_j0
.Ltr_j0d:
	s_sub_u32 s4, s4, 0x980
	s_cmpk_ge_u32 s4, 0x2300
	s_cbranch_scc1 .Ltr_done
	s_mov_b32 s5, s4
.Ltr_p_m0:
	s_cmpk_lt_u32 s5, 0x1500
	s_cbranch_scc1 .Ltr_p_d0
	s_sub_u32 s5, s5, 0x1500
	s_branch .Ltr_p_m1
.Ltr_p_m1:
	s_cmpk_lt_u32 s5, 0x200
	s_cbranch_scc1 .Ltr_p_d1
	s_sub_u32 s5, s5, 0x200
	s_branch .Ltr_p_m2
.Ltr_p_m2:
	s_cmpk_lt_u32 s5, 0x400
	s_cbranch_scc1 .Ltr_p_d2
	s_sub_u32 s5, s5, 0x400
	s_branch .Ltr_p_m3

.Ltr_p_d0:
	s_mul_i32 s6, s5, 6242
	s_lshr_b32 s6, s6, 20
	s_mul_i32 s7, s6, 168
	s_sub_u32 s7, s5, s7
	s_mov_b32 s12, 0xa800
	s_mul_i32 s8, s6, 0x2a0000
	s_lshl_b32 s9, s7, 8
	s_add_u32 s8, s8, s9
	s_add_u32 s10, s30, s8
	s_addc_u32 s11, s31, 0
	s_lshl_b32 s8, s7, 18
	s_lshl_b32 s9, s6, 7
	s_add_u32 s8, s8, s9
	s_add_u32 s8, s8, 0x13288000
	s_add_u32 s14, s94, s8
	s_addc_u32 s15, s95, 0
	s_branch .Ltr_p_end
.Ltr_p_d1:
	s_lshr_b32 s6, s5, 4
	s_and_b32 s7, s5, 15
	s_mov_b32 s12, 0x1000
	s_mul_i32 s8, s6, 0x40000
	s_lshl_b32 s9, s7, 8
	s_add_u32 s8, s8, s9
	s_add_u32 s10, s32, s8
	s_addc_u32 s11, s33, 0
	s_lshl_b32 s8, s7, 18
	s_lshl_b32 s9, s6, 7
	s_add_u32 s8, s8, s9
	s_add_u32 s8, s8, 0x17e88000
	s_add_u32 s14, s94, s8
	s_addc_u32 s15, s95, 0
	s_branch .Ltr_p_end
.Ltr_p_d2:
	s_lshr_b32 s6, s5, 5
	s_and_b32 s7, s5, 31
	s_mov_b32 s12, 0x2000
	s_mul_i32 s8, s6, 0x80000
	s_lshl_b32 s9, s7, 8
	s_add_u32 s8, s8, s9
	s_add_u32 s10, s34, s8
	s_addc_u32 s11, s35, 0
	s_lshl_b32 s8, s7, 18
	s_lshl_b32 s9, s6, 7
	s_add_u32 s8, s8, s9
	s_add_u32 s8, s8, 0x18288000
	s_add_u32 s14, s94, s8
	s_addc_u32 s15, s95, 0
	s_branch .Ltr_p_end
.Ltr_p_d3:
	s_lshr_b32 s6, s5, 5
	s_and_b32 s7, s5, 31
	s_mov_b32 s12, 0x2000
	s_mul_i32 s8, s6, 0x80000
	s_lshl_b32 s9, s7, 8
	s_add_u32 s8, s8, s9
	s_add_u32 s10, s36, s8
	s_addc_u32 s11, s37, 0
	s_lshl_b32 s8, s7, 18
	s_lshl_b32 s9, s6, 7
	s_add_u32 s8, s8, s9
	s_add_u32 s8, s8, 0x18a88000
	s_add_u32 s14, s94, s8
	s_addc_u32 s15, s95, 0
	s_branch .Ltr_p_end
.Ltr_p_d4:
	s_lshr_b32 s6, s5, 5
	s_and_b32 s7, s5, 31
	s_mov_b32 s12, 0x2000
	s_mul_i32 s8, s6, 0x80000
	s_lshl_b32 s9, s7, 8
	s_add_u32 s8, s8, s9
	s_add_u32 s10, s38, s8
	s_addc_u32 s11, s39, 0
	s_lshl_b32 s8, s7, 18
	s_lshl_b32 s9, s6, 7
	s_add_u32 s8, s8, s9
	s_add_u32 s8, s8, 0x19288000
	s_add_u32 s14, s94, s8
	s_addc_u32 s15, s95, 0
.Ltr_p_end:
	s_mov_b64 s[16:17], s[14:15]
	v_mad_u32_u24 v4, v78, s12, v1
	v_mad_u32_u24 v5, v79, s12, v1
	v_mad_u32_u24 v6, v80, s12, v1
	v_mad_u32_u24 v7, v81, s12, v1
	global_load_dwordx4 v[16:19], v4, s[10:11]
	global_load_dwordx4 v[20:23], v5, s[10:11]
	global_load_dwordx4 v[24:27], v6, s[10:11]
	global_load_dwordx4 v[28:31], v7, s[10:11]
.Ltr_loop:
	s_add_u32 s18, s4, s3
	s_cmpk_lt_u32 s18, 0x2300
	s_cselect_b32 s19, s18, s4
	s_mov_b32 s5, s19

.Ltr_a_end:
	v_mad_u32_u24 v4, v78, s12, v1
	v_mad_u32_u24 v5, v79, s12, v1
	v_mad_u32_u24 v6, v80, s12, v1
	v_mad_u32_u24 v7, v81, s12, v1
	global_load_dwordx4 v[32:35], v4, s[10:11]
	global_load_dwordx4 v[36:39], v5, s[10:11]
	global_load_dwordx4 v[40:43], v6, s[10:11]
	global_load_dwordx4 v[44:47], v7, s[10:11]
	s_waitcnt vmcnt(4)
	ds_write2_b32 v8, v16, v17 offset1:1
	ds_write2_b32 v8, v18, v19 offset0:2 offset1:3
	ds_write2_b32 v9, v20, v21 offset1:1
	ds_write2_b32 v9, v22, v23 offset0:2 offset1:3
	ds_write2_b32 v10, v24, v25 offset1:1
	ds_write2_b32 v10, v26, v27 offset0:2 offset1:3
	ds_write2_b32 v11, v28, v29 offset1:1
	ds_write2_b32 v11, v30, v31 offset0:2 offset1:3
	s_waitcnt lgkmcnt(0)
	s_barrier
	ds_read2_b32 v[48:49], v12 offset1:65
	ds_read2_b32 v[50:51], v12 offset0:130 offset1:195
	ds_read2_b32 v[52:53], v13 offset1:65
	ds_read2_b32 v[54:55], v13 offset0:130 offset1:195
	ds_read2_b32 v[56:57], v12 offset0:32 offset1:97
	ds_read2_b32 v[58:59], v12 offset0:162 offset1:227
	ds_read2_b32 v[60:61], v13 offset0:32 offset1:97
	ds_read2_b32 v[62:63], v13 offset0:162 offset1:227
	s_waitcnt lgkmcnt(4)
	v_cvt_pk_bf16_f32 v64, v48, v49
	v_cvt_pk_bf16_f32 v65, v50, v51
	v_cvt_pk_bf16_f32 v66, v52, v53
	v_cvt_pk_bf16_f32 v67, v54, v55
	s_waitcnt lgkmcnt(0)
	v_cvt_pk_bf16_f32 v68, v56, v57
	v_cvt_pk_bf16_f32 v69, v58, v59
	v_cvt_pk_bf16_f32 v70, v60, v61
	v_cvt_pk_bf16_f32 v71, v62, v63
	global_store_dwordx4 v14, v[64:67], s[16:17]
	global_store_dwordx4 v15, v[68:71], s[16:17]
	s_mov_b64 s[16:17], s[14:15]
	s_mov_b32 s4, s18
	s_cmpk_lt_u32 s4, 0x2300
	s_cbranch_scc0 .Ltr_drain
	s_add_u32 s18, s4, s3
	s_cmpk_lt_u32 s18, 0x2300
	s_cselect_b32 s19, s18, s4
	s_mov_b32 s5, s19

.Ltr_b_end:
	v_mad_u32_u24 v4, v78, s12, v1
	v_mad_u32_u24 v5, v79, s12, v1
	v_mad_u32_u24 v6, v80, s12, v1
	v_mad_u32_u24 v7, v81, s12, v1
	global_load_dwordx4 v[16:19], v4, s[10:11]
	global_load_dwordx4 v[20:23], v5, s[10:11]
	global_load_dwordx4 v[24:27], v6, s[10:11]
	global_load_dwordx4 v[28:31], v7, s[10:11]
	s_waitcnt vmcnt(4)
	ds_write2_b32 v72, v32, v33 offset1:1
	ds_write2_b32 v72, v34, v35 offset0:2 offset1:3
	ds_write2_b32 v73, v36, v37 offset1:1
	ds_write2_b32 v73, v38, v39 offset0:2 offset1:3
	ds_write2_b32 v74, v40, v41 offset1:1
	ds_write2_b32 v74, v42, v43 offset0:2 offset1:3
	ds_write2_b32 v75, v44, v45 offset1:1
	ds_write2_b32 v75, v46, v47 offset0:2 offset1:3
	s_waitcnt lgkmcnt(0)
	s_barrier
	ds_read2_b32 v[48:49], v76 offset1:65
	ds_read2_b32 v[50:51], v76 offset0:130 offset1:195
	ds_read2_b32 v[52:53], v77 offset1:65
	ds_read2_b32 v[54:55], v77 offset0:130 offset1:195
	ds_read2_b32 v[56:57], v76 offset0:32 offset1:97
	ds_read2_b32 v[58:59], v76 offset0:162 offset1:227
	ds_read2_b32 v[60:61], v77 offset0:32 offset1:97
	ds_read2_b32 v[62:63], v77 offset0:162 offset1:227
	s_waitcnt lgkmcnt(4)
	v_cvt_pk_bf16_f32 v64, v48, v49
	v_cvt_pk_bf16_f32 v65, v50, v51
	v_cvt_pk_bf16_f32 v66, v52, v53
	v_cvt_pk_bf16_f32 v67, v54, v55
	s_waitcnt lgkmcnt(0)
	v_cvt_pk_bf16_f32 v68, v56, v57
	v_cvt_pk_bf16_f32 v69, v58, v59
	v_cvt_pk_bf16_f32 v70, v60, v61
	v_cvt_pk_bf16_f32 v71, v62, v63
	global_store_dwordx4 v14, v[64:67], s[16:17]
	global_store_dwordx4 v15, v[68:71], s[16:17]
	s_mov_b64 s[16:17], s[14:15]
	s_mov_b32 s4, s18
	s_cmpk_lt_u32 s4, 0x2300
	s_cbranch_scc0 .Ltr_drain
	s_branch .Ltr_loop
.Ltr_drain:
	s_waitcnt vmcnt(0)
	s_barrier
.Ltr_done:
	v_lshlrev_b32_e32 v69, 3, v204
	v_and_b32_e32 v4, 56, v69
	v_lshlrev_b32_e32 v16, 1, v4
	v_mov_b32_e32 v17, 0
	v_lshl_add_u64 v[0:1], s[94:95], 0, v[16:17]
	s_mov_b64 s[4:5], 0x19288000
	v_lshl_add_u64 v[18:19], v[0:1], 0, s[4:5]
	s_mov_b64 s[4:5], 0x18a88000
	v_lshl_add_u64 v[20:21], v[0:1], 0, s[4:5]
	s_mov_b64 s[4:5], 0x18288000
	v_lshl_add_u64 v[22:23], v[0:1], 0, s[4:5]
	s_mov_b64 s[4:5], 0x17e88000
	v_lshlrev_b32_e32 v2, 2, v204
	v_lshl_add_u64 v[24:25], v[0:1], 0, s[4:5]
	s_mov_b64 s[4:5], 0x13288000
	v_lshl_add_u64 v[26:27], v[0:1], 0, s[4:5]
	v_and_b32_e32 v0, 0xfc, v2
	v_lshlrev_b32_e32 v16, 1, v0
	v_lshl_add_u64 v[2:3], s[94:95], 0, v[16:17]
	s_mov_b64 s[4:5], 0x19a88000
	v_and_b32_e32 v1, 7, v204
	v_lshl_add_u64 v[28:29], v[2:3], 0, s[4:5]
	s_mov_b64 s[4:5], 0x15c88000
	v_cvt_f32_ubyte0_e32 v1, v1
	v_lshl_add_u64 v[30:31], v[2:3], 0, s[4:5]
	v_mul_f32_e32 v2, 0xc01773da, v1
	s_mov_b32 s3, 0xc2fc0000
	s_load_dwordx16 s[16:31], s[0:1], 0xc0
	s_add_u32 s14, s94, 0x19e88000
	v_mov_b32_e32 v3, 0x42800000
	v_cmp_gt_f32_e32 vcc, s3, v2
	s_addc_u32 s15, s95, 0
	s_load_dwordx16 s[36:51], s[0:1], 0x0
	v_cndmask_b32_e32 v3, 0, v3, vcc
	s_add_u32 s34, s94, 0x1c908000
	v_lshlrev_b32_e32 v2, 4, v204
	v_fmac_f32_e32 v3, 0xc01773da, v1
	s_addc_u32 s35, s95, 0
	v_and_b32_e32 v2, 0xf0, v2
	v_exp_f32_e32 v1, v3
	v_mov_b32_e32 v3, v17
	s_waitcnt lgkmcnt(0)
	v_lshl_add_u64 v[58:59], s[18:19], 0, v[2:3]
	s_add_u32 s18, s94, 0x1c708000
	v_lshlrev_b32_e32 v16, 2, v0
	s_addc_u32 s19, s95, 0
	v_lshl_add_u64 v[36:37], s[50:51], 0, v[16:17]
	v_lshl_add_u64 v[56:57], s[40:41], 0, v[16:17]
	s_add_u32 s29, s94, 0x1b008000
	v_lshl_add_u64 v[60:61], s[88:89], 0, v[2:3]
	s_load_dword s88, s[0:1], 0x120
	s_load_dwordx16 s[36:51], s[0:1], 0x40
	v_not_b32_e32 v70, 63
	v_lshl_add_u64 v[32:33], s[86:87], 0, v[16:17]
	s_mov_b64 s[4:5], 0x1000
	s_addc_u32 s64, s95, 0
	v_cndmask_b32_e32 v5, 0, v70, vcc
	v_lshl_add_u64 v[34:35], v[32:33], 0, s[4:5]
	v_lshl_add_u64 v[38:39], v[36:37], 0, s[4:5]
	s_mov_b64 s[4:5], 0x1400
	s_add_u32 s87, s94, 0x19f08000
	v_lshl_add_u64 v[40:41], v[32:33], 0, s[4:5]
	v_lshl_add_u64 v[42:43], v[36:37], 0, s[4:5]
	s_mov_b64 s[4:5], 0x1800
	v_lshrrev_b32_e32 v6, 3, v204
	v_ldexp_f32 v77, v1, v5
	v_lshl_add_u32 v1, s2, 8, v204
	s_addc_u32 s96, s95, 0
	v_lshl_add_u64 v[44:45], v[32:33], 0, s[4:5]
	v_lshl_add_u64 v[46:47], v[36:37], 0, s[4:5]
	s_mov_b64 s[4:5], 0x1c00
	v_lshrrev_b32_e32 v71, 4, v204
	v_lshl_add_u64 v[54:55], s[20:21], 0, v[2:3]
	v_add_u32_e32 v16, 0xffca6000, v1
	v_lshlrev_b32_e32 v78, 11, v6
	v_and_b32_e32 v1, 16, v204
	v_and_b32_e32 v5, 32, v204
	s_add_u32 s20, s94, 0x1cb28000
	v_lshrrev_b32_e32 v68, 6, v204
	v_lshl_add_u64 v[48:49], v[32:33], 0, s[4:5]
	v_lshl_add_u64 v[50:51], v[36:37], 0, s[4:5]
	v_add_u32_e32 v72, 32, v2
	v_mul_u32_u24_e32 v73, 0x104, v71
	v_add_u32_e32 v74, 16, v71
	v_add_u32_e32 v75, 32, v71
	v_add_u32_e32 v76, 48, v71
	v_lshl_add_u64 v[52:53], s[24:25], 0, v[2:3]
	v_add_u32_e32 v79, 0x10000, v78
	v_mul_u32_u24_e32 v80, 0x104, v4
	v_lshl_add_u32 v81, v6, 2, 32
	s_addc_u32 s21, s95, 0
	v_mov_b32_e32 v82, 0x358637bd
	s_waitcnt lgkmcnt(0)
	v_lshl_add_u64 v[62:63], s[36:37], 0, v[2:3]
	v_mov_b32_e32 v83, 0x3c0881c4
	s_lshl_b32 s60, s2, 13
	v_mov_b32_e32 v84, 0xbab64f3b
	s_lshl_b32 s61, s88, 13
	v_not_b32_e32 v85, 31
	s_lshl_b32 s89, s2, 1
	v_mov_b32_e32 v86, 0x7fc00000
	s_lshl_b32 s97, s88, 1
	v_lshlrev_b32_e32 v64, 2, v0
	s_lshl_b32 s33, s2, 2
	s_lshl_b32 s3, s88, 2
	s_lshl_b32 s86, s88, 8
	s_movk_i32 s16, 0x2000
	s_movk_i32 s17, 0x4000
	s_movk_i32 s22, 0x6000
	s_movk_i32 s23, 0x1000
	s_mov_b32 s26, 0x800000
	s_brev_b32 s27, 1
	s_mov_b32 s28, s2
	s_mov_b32 s25, 0
	v_cmp_eq_u32_e64 s[4:5], 0, v1
	v_cmp_eq_u32_e64 s[6:7], 0, v5
	s_mov_b64 s[30:31], 0x2000
	s_mov_b64 s[62:63], 0x4000
	s_mov_b64 s[52:53], 0x6000
	s_branch .LBB0_24

.LBB0_715:
	s_add_i32 s16, s22, s33
	s_cmpk_gt_i32 s16, 0x7f
	s_mov_b64 s[30:31], -1
	s_cbranch_scc1 .LBB0_714
	s_ashr_i32 s30, s16, 31
	s_lshr_b32 s30, s30, 25
	s_add_i32 s30, s16, s30
	s_ashr_i32 s61, s30, 7
	s_and_b32 s30, s30, 0xffffff80
	s_lshl_b32 s31, s61, 3
	s_sub_i32 s30, s16, s30
	s_sub_i32 s34, 8, s31
	s_cmpk_gt_i32 s16, 0x7f
	s_cselect_b32 s16, s34, 8
	s_abs_i32 s34, s16
	v_cvt_f32_u32_e32 v0, s34
	s_sub_i32 s41, 0, s34
	s_abs_i32 s35, s30
	s_xor_b32 s40, s30, s16
	v_rcp_iflag_f32_e32 v0, v0
	s_ashr_i32 s40, s40, 31
	v_mov_b32_e32 v10, v204
	v_mul_f32_e32 v0, 0x4f7ffffe, v0
	v_cvt_u32_f32_e32 v0, v0
	v_ashrrev_i32_e32 v1, 6, v10
	v_lshlrev_b32_e32 v3, 9, v10
	v_and_b32_e32 v3, 0x7800, v3
	v_readfirstlane_b32 s42, v0
	s_mul_i32 s41, s41, s42
	s_mul_hi_u32 s41, s42, s41
	s_add_i32 s42, s42, s41
	s_mul_hi_u32 s41, s35, s42
	s_mul_i32 s42, s41, s34
	s_sub_i32 s35, s35, s42
	s_add_i32 s43, s41, 1
	s_sub_i32 s42, s35, s34
	s_cmp_ge_u32 s35, s34
	s_cselect_b32 s41, s43, s41
	s_cselect_b32 s35, s42, s35
	s_add_i32 s42, s41, 1
	s_cmp_ge_u32 s35, s34
	s_cselect_b32 s34, s42, s41
	s_xor_b32 s34, s34, s40
	s_sub_i32 s34, s34, s40
	s_mul_i32 s62, s16, s34
	s_sub_i32 s55, s30, s62
	s_add_i32 s55, s55, s31
	s_lshl_b32 s16, s55, 6
	s_add_i32 s40, s16, 0x2000
	s_ashr_i32 s41, s40, 31
	v_bfe_u32 v0, v10, 4, 2
	s_lshl_b64 s[30:31], s[40:41], 11
	s_lshl_b64 s[40:41], s[40:41], 12
	v_bitop3_b32 v0, v0, v10, 3 bitop3:0x78
	s_add_u32 s40, s50, s40
	v_lshlrev_b32_e32 v2, 3, v0
	v_lshlrev_b32_e32 v0, 15, v1
	v_lshlrev_b32_e32 v4, 16, v1
	v_lshlrev_b32_e32 v1, 10, v1
	s_addc_u32 s41, s51, s41
	s_ashr_i32 s35, s34, 31
	v_or3_b32 v0, v3, v0, v2
	v_add_u32_e32 v40, 32, v1
	s_lshl_b64 s[42:43], s[34:35], 19
	v_or3_b32 v2, v3, v4, v2
	v_add_u32_e32 v41, v40, v1
	v_ashrrev_i32_e32 v1, 31, v0
	s_add_u32 s44, s47, s42
	v_add_u32_e32 v8, 0x1000, v41
	v_lshlrev_b64 v[0:1], 1, v[0:1]
	v_ashrrev_i32_e32 v3, 31, v2
	v_readfirstlane_b32 s35, v40
	s_addc_u32 s45, s49, s43
	v_lshl_add_u64 v[4:5], s[40:41], 0, v[0:1]
	v_lshlrev_b64 v[2:3], 1, v[2:3]
	s_mov_b32 m0, s35
	v_readfirstlane_b32 s35, v8
	v_add_u32_e32 v11, 0x1400, v41
	v_lshl_add_u64 v[6:7], s[44:45], 0, v[2:3]
	global_load_lds_dwordx4 v[4:5], off
	s_mov_b32 m0, s35
	v_readfirstlane_b32 s35, v11
	v_add_u32_e32 v11, 0x3000, v40
	global_load_lds_dwordx4 v[6:7], off
	v_lshl_add_u64 v[8:9], v[6:7], 0, s[6:7]
	s_mov_b32 m0, s35
	v_readfirstlane_b32 s35, v11
	v_add_u32_e32 v11, 0x4000, v41
	global_load_lds_dwordx4 v[8:9], off
	v_lshl_add_u64 v[8:9], v[4:5], 0, 64
	s_mov_b32 m0, s35
	v_readfirstlane_b32 s35, v11
	v_add_u32_e32 v11, 0x4400, v41
	global_load_lds_dwordx4 v[8:9], off
	v_lshl_add_u64 v[8:9], v[6:7], 0, 64
	s_mov_b32 m0, s35
	v_readfirstlane_b32 s35, v11
	global_load_lds_dwordx4 v[8:9], off
	v_lshl_add_u64 v[8:9], v[6:7], 0, s[8:9]
	s_mov_b32 m0, s35
	v_lshl_add_u64 v[4:5], v[4:5], 0, s[10:11]
	global_load_lds_dwordx4 v[8:9], off
	v_add_u32_e32 v8, 0x6000, v40
	s_add_u32 s40, s94, s42
	v_readfirstlane_b32 s35, v8
	v_add_u32_e32 v8, 0x7000, v41
	s_mov_b32 m0, s35
	v_readfirstlane_b32 s35, v8
	global_load_lds_dwordx4 v[4:5], off
	v_lshl_add_u64 v[4:5], v[6:7], 0, s[10:11]
	s_mov_b32 m0, s35
	s_addc_u32 s41, s95, s43
	global_load_lds_dwordx4 v[4:5], off
	v_lshl_add_u64 v[4:5], v[6:7], 0, s[12:13]
	v_add_u32_e32 v6, 0x7400, v41
	v_lshl_add_u64 v[32:33], s[40:41], 0, v[2:3]
	v_readfirstlane_b32 s35, v6
	s_mov_b32 m0, s35
	s_sub_i32 s40, s48, s62
	global_load_lds_dwordx4 v[4:5], off
	s_mulk_i32 s61, 0x78
	s_sub_i32 s40, s40, s61
	s_lshl_b32 s40, s40, 6
	v_and_b32_e32 v4, 31, v10
	v_lshrrev_b32_e32 v6, 2, v10
	s_addk_i32 s40, 0x2000
	v_and_or_b32 v4, v6, s54, v4
	s_ashr_i32 s41, s40, 31
	v_bfe_u32 v5, v10, 5, 1
	v_lshlrev_b32_e32 v42, 6, v4
	v_lshlrev_b32_e32 v4, 6, v10
	s_lshl_b64 s[40:41], s[40:41], 12
	v_bfe_u32 v7, v10, 2, 2
	v_and_b32_e32 v43, 0x17c0, v4
	v_bitop3_b32 v4, v5, v6, 3 bitop3:0x78
	s_add_u32 s40, s94, s40
	v_lshlrev_b32_e32 v44, 4, v4
	v_bitop3_b32 v4, v5, v7, 2 bitop3:0x36
	s_addc_u32 s41, s95, s41
	v_mov_b32_e32 v16, 0
	s_mov_b32 s60, 0
	s_mov_b32 s35, 1
	v_lshlrev_b32_e32 v45, 4, v4
	v_lshl_add_u64 v[34:35], s[40:41], 0, v[0:1]
	s_mov_b64 s[40:41], 0
	v_mov_b32_e32 v17, v16
	v_mov_b32_e32 v18, v16
	v_mov_b32_e32 v19, v16
	v_mov_b32_e32 v20, v16
	v_mov_b32_e32 v21, v16
	v_mov_b32_e32 v22, v16
	v_mov_b32_e32 v23, v16
	v_mov_b32_e32 v24, v16
	v_mov_b32_e32 v25, v16
	v_mov_b32_e32 v26, v16
	v_mov_b32_e32 v27, v16
	v_mov_b32_e32 v28, v16
	v_mov_b32_e32 v29, v16
	v_mov_b32_e32 v30, v16
	v_mov_b32_e32 v31, v16
	v_mov_b32_e32 v0, v16
	v_mov_b32_e32 v1, v16
	v_mov_b32_e32 v2, v16
	v_mov_b32_e32 v3, v16
	v_mov_b32_e32 v4, v16
	v_mov_b32_e32 v5, v16
	v_mov_b32_e32 v6, v16
	v_mov_b32_e32 v7, v16
	v_mov_b32_e32 v8, v16
	v_mov_b32_e32 v9, v16
	v_mov_b32_e32 v10, v16
	v_mov_b32_e32 v11, v16
	v_mov_b32_e32 v12, v16
	v_mov_b32_e32 v13, v16
	v_mov_b32_e32 v14, v16
	v_mov_b32_e32 v15, v16
	v_add3_u32 v184, v42, v44, 32
	v_add3_u32 v185, v42, v45, 32
	v_add_u32_e32 v186, 0x1020, v43
	v_add_u32_e32 v187, v186, v45
	v_add_u32_e32 v186, v186, v44
	v_subrev_u32_e32 v188, s94, v34
	v_subrev_u32_e32 v189, s94, v32
	v_add_u32_e32 v188, 0x15c88000, v188
	v_add_u32_e32 v189, 0x18a88000, v189
	v_add_u32_e32 v190, 0x10000, v189
	v_readfirstlane_b32 s80, v40
	v_readfirstlane_b32 s81, v41
	s_add_u32 s76, s94, 256
	s_addc_u32 s77, s95, 0
	s_add_u32 s78, s94, 192
	s_addc_u32 s79, s95, 0
	s_add_u32 s81, s81, 0x1000
	s_add_u32 m0, s80, 0x9000
	s_nop 0
	global_load_lds_dwordx4 v188, s[78:79]
	s_add_u32 m0, s81, 0x9000
	s_nop 0
	global_load_lds_dwordx4 v189, s[78:79]
	s_add_u32 m0, s81, 0x9400
	s_nop 0
	global_load_lds_dwordx4 v190, s[78:79]
	s_add_u32 s78, s78, 128
	s_addc_u32 s79, s79, 0
	s_add_u32 m0, s80, 0xc000
	s_nop 0
	global_load_lds_dwordx4 v188, s[76:77]
	s_add_u32 m0, s80, 0xf000
	s_nop 0
	global_load_lds_dwordx4 v188, s[78:79]
	s_add_u32 m0, s81, 0xc000
	s_nop 0
	global_load_lds_dwordx4 v189, s[76:77]
	s_add_u32 m0, s81, 0xf000
	s_nop 0
	global_load_lds_dwordx4 v189, s[78:79]
	s_add_u32 m0, s81, 0xc400
	s_nop 0
	global_load_lds_dwordx4 v190, s[76:77]
	s_add_u32 m0, s81, 0xf400
	s_nop 0
	global_load_lds_dwordx4 v190, s[78:79]
	s_add_u32 s76, s76, 128
	s_addc_u32 s77, s77, 0
	s_add_u32 s78, s78, 128
	s_addc_u32 s79, s79, 0
	s_waitcnt vmcnt(15)
	s_barrier
	ds_read_b128 v[160:163], v186 offset:0
	ds_read_b128 v[164:167], v186 offset:2048
	ds_read_b128 v[168:171], v184 offset:0
	s_waitcnt lgkmcnt(0)
	s_setprio 1
	v_mfma_f32_32x32x16_bf16 v[16:31], v[168:171], v[160:163], v[16:31]
	v_mfma_f32_32x32x16_bf16 v[0:15], v[168:171], v[164:167], v[0:15]
	s_setprio 0
	ds_read_b128 v[172:175], v187 offset:0
	ds_read_b128 v[176:179], v187 offset:2048
	ds_read_b128 v[180:183], v185 offset:0
	s_waitcnt vmcnt(12) lgkmcnt(0)
	s_barrier
	ds_read_b128 v[160:163], v186 offset:12288
	ds_read_b128 v[164:167], v186 offset:14336
	ds_read_b128 v[168:171], v184 offset:12288
	s_setprio 1
	v_mfma_f32_32x32x16_bf16 v[16:31], v[180:183], v[172:175], v[16:31]
	v_mfma_f32_32x32x16_bf16 v[0:15], v[180:183], v[176:179], v[0:15]
	s_setprio 0
	s_waitcnt lgkmcnt(0)
	s_setprio 1
	v_mfma_f32_32x32x16_bf16 v[16:31], v[168:171], v[160:163], v[16:31]
	v_mfma_f32_32x32x16_bf16 v[0:15], v[168:171], v[164:167], v[0:15]
	s_setprio 0
	ds_read_b128 v[172:175], v187 offset:12288
	ds_read_b128 v[176:179], v187 offset:14336
	ds_read_b128 v[180:183], v185 offset:12288
	s_waitcnt vmcnt(9) lgkmcnt(0)
	s_barrier
	ds_read_b128 v[160:163], v186 offset:24576
	ds_read_b128 v[164:167], v186 offset:26624
	ds_read_b128 v[168:171], v184 offset:24576
	s_setprio 1
	v_mfma_f32_32x32x16_bf16 v[16:31], v[180:183], v[172:175], v[16:31]
	v_mfma_f32_32x32x16_bf16 v[0:15], v[180:183], v[176:179], v[0:15]
	s_setprio 0
	s_add_u32 m0, s80, 0x0
	s_nop 0
	global_load_lds_dwordx4 v188, s[76:77]
	s_add_u32 m0, s80, 0x3000
	s_nop 0
	global_load_lds_dwordx4 v188, s[78:79]
	s_waitcnt lgkmcnt(0)
	s_setprio 1
	v_mfma_f32_32x32x16_bf16 v[16:31], v[168:171], v[160:163], v[16:31]
	v_mfma_f32_32x32x16_bf16 v[0:15], v[168:171], v[164:167], v[0:15]
	s_setprio 0
	ds_read_b128 v[172:175], v187 offset:24576
	ds_read_b128 v[176:179], v187 offset:26624
	ds_read_b128 v[180:183], v185 offset:24576
	s_add_u32 m0, s81, 0x0
	s_nop 0
	global_load_lds_dwordx4 v189, s[76:77]
	s_add_u32 m0, s81, 0x3000
	s_nop 0
	global_load_lds_dwordx4 v189, s[78:79]
	s_add_u32 m0, s81, 0x400
	s_nop 0
	global_load_lds_dwordx4 v190, s[76:77]
	s_add_u32 m0, s81, 0x3400
	s_nop 0
	global_load_lds_dwordx4 v190, s[78:79]
	s_add_u32 s76, s76, 128
	s_addc_u32 s77, s77, 0
	s_add_u32 s78, s78, 128
	s_addc_u32 s79, s79, 0
	s_waitcnt vmcnt(12) lgkmcnt(0)
	s_barrier
	ds_read_b128 v[160:163], v186 offset:36864
	ds_read_b128 v[164:167], v186 offset:38912
	ds_read_b128 v[168:171], v184 offset:36864
	s_setprio 1
	v_mfma_f32_32x32x16_bf16 v[16:31], v[180:183], v[172:175], v[16:31]
	v_mfma_f32_32x32x16_bf16 v[0:15], v[180:183], v[176:179], v[0:15]
	s_setprio 0
	s_waitcnt lgkmcnt(0)
	s_setprio 1
	v_mfma_f32_32x32x16_bf16 v[16:31], v[168:171], v[160:163], v[16:31]
	v_mfma_f32_32x32x16_bf16 v[0:15], v[168:171], v[164:167], v[0:15]
	s_setprio 0
	ds_read_b128 v[172:175], v187 offset:36864
	ds_read_b128 v[176:179], v187 offset:38912
	ds_read_b128 v[180:183], v185 offset:36864
	s_waitcnt vmcnt(7) lgkmcnt(0)
	s_barrier
	ds_read_b128 v[160:163], v186 offset:49152
	ds_read_b128 v[164:167], v186 offset:51200
	ds_read_b128 v[168:171], v184 offset:49152
	s_setprio 1
	v_mfma_f32_32x32x16_bf16 v[16:31], v[180:183], v[172:175], v[16:31]
	v_mfma_f32_32x32x16_bf16 v[0:15], v[180:183], v[176:179], v[0:15]
	s_setprio 0
	s_add_u32 m0, s80, 0x6000
	s_nop 0
	global_load_lds_dwordx4 v188, s[76:77]
	s_add_u32 m0, s80, 0x9000
	s_nop 0
	global_load_lds_dwordx4 v188, s[78:79]
	s_waitcnt lgkmcnt(0)
	s_setprio 1
	v_mfma_f32_32x32x16_bf16 v[16:31], v[168:171], v[160:163], v[16:31]
	v_mfma_f32_32x32x16_bf16 v[0:15], v[168:171], v[164:167], v[0:15]
	s_setprio 0
	ds_read_b128 v[172:175], v187 offset:49152
	ds_read_b128 v[176:179], v187 offset:51200
	ds_read_b128 v[180:183], v185 offset:49152
	s_add_u32 m0, s81, 0x6000
	s_nop 0
	global_load_lds_dwordx4 v189, s[76:77]
	s_add_u32 m0, s81, 0x9000
	s_nop 0
	global_load_lds_dwordx4 v189, s[78:79]
	s_add_u32 m0, s81, 0x6400
	s_nop 0
	global_load_lds_dwordx4 v190, s[76:77]
	s_add_u32 m0, s81, 0x9400
	s_nop 0
	global_load_lds_dwordx4 v190, s[78:79]
	s_add_u32 s76, s76, 128
	s_addc_u32 s77, s77, 0
	s_add_u32 s78, s78, 128
	s_addc_u32 s79, s79, 0
	s_waitcnt vmcnt(12) lgkmcnt(0)
	s_barrier
	ds_read_b128 v[160:163], v186 offset:61440
	ds_read_b128 v[164:167], v186 offset:63488
	ds_read_b128 v[168:171], v184 offset:61440
	s_setprio 1
	v_mfma_f32_32x32x16_bf16 v[16:31], v[180:183], v[172:175], v[16:31]
	v_mfma_f32_32x32x16_bf16 v[0:15], v[180:183], v[176:179], v[0:15]
	s_setprio 0
	s_waitcnt lgkmcnt(0)
	s_setprio 1
	v_mfma_f32_32x32x16_bf16 v[16:31], v[168:171], v[160:163], v[16:31]
	v_mfma_f32_32x32x16_bf16 v[0:15], v[168:171], v[164:167], v[0:15]
	s_setprio 0
	ds_read_b128 v[172:175], v187 offset:61440
	ds_read_b128 v[176:179], v187 offset:63488
	ds_read_b128 v[180:183], v185 offset:61440
	s_mov_b32 s82, 9
.Lp5s_kloop:
	s_waitcnt vmcnt(6) lgkmcnt(0)
	s_barrier
	ds_read_b128 v[160:163], v186 offset:0
	ds_read_b128 v[164:167], v186 offset:2048
	ds_read_b128 v[168:171], v184 offset:0
	s_setprio 1
	v_mfma_f32_32x32x16_bf16 v[16:31], v[180:183], v[172:175], v[16:31]
	v_mfma_f32_32x32x16_bf16 v[0:15], v[180:183], v[176:179], v[0:15]
	s_setprio 0
	s_add_u32 m0, s80, 0xc000
	s_nop 0
	global_load_lds_dwordx4 v188, s[76:77]
	s_add_u32 m0, s80, 0xf000
	s_nop 0
	global_load_lds_dwordx4 v188, s[78:79]
	s_waitcnt lgkmcnt(0)
	s_setprio 1
	v_mfma_f32_32x32x16_bf16 v[16:31], v[168:171], v[160:163], v[16:31]
	v_mfma_f32_32x32x16_bf16 v[0:15], v[168:171], v[164:167], v[0:15]
	s_setprio 0
	ds_read_b128 v[172:175], v187 offset:0
	ds_read_b128 v[176:179], v187 offset:2048
	ds_read_b128 v[180:183], v185 offset:0
	s_add_u32 m0, s81, 0xc000
	s_nop 0
	global_load_lds_dwordx4 v189, s[76:77]
	s_add_u32 m0, s81, 0xf000
	s_nop 0
	global_load_lds_dwordx4 v189, s[78:79]
	s_add_u32 m0, s81, 0xc400
	s_nop 0
	global_load_lds_dwordx4 v190, s[76:77]
	s_add_u32 m0, s81, 0xf400
	s_nop 0
	global_load_lds_dwordx4 v190, s[78:79]
	s_add_u32 s76, s76, 128
	s_addc_u32 s77, s77, 0
	s_add_u32 s78, s78, 128
	s_addc_u32 s79, s79, 0
	s_waitcnt lgkmcnt(0)
	s_barrier
	ds_read_b128 v[160:163], v186 offset:12288
	ds_read_b128 v[164:167], v186 offset:14336
	ds_read_b128 v[168:171], v184 offset:12288
	s_setprio 1
	v_mfma_f32_32x32x16_bf16 v[16:31], v[180:183], v[172:175], v[16:31]
	v_mfma_f32_32x32x16_bf16 v[0:15], v[180:183], v[176:179], v[0:15]
	s_setprio 0
	s_waitcnt lgkmcnt(0)
	s_setprio 1
	v_mfma_f32_32x32x16_bf16 v[16:31], v[168:171], v[160:163], v[16:31]
	v_mfma_f32_32x32x16_bf16 v[0:15], v[168:171], v[164:167], v[0:15]
	s_setprio 0
	ds_read_b128 v[172:175], v187 offset:12288
	ds_read_b128 v[176:179], v187 offset:14336
	ds_read_b128 v[180:183], v185 offset:12288
	s_waitcnt vmcnt(6) lgkmcnt(0)
	s_barrier
	ds_read_b128 v[160:163], v186 offset:24576
	ds_read_b128 v[164:167], v186 offset:26624
	ds_read_b128 v[168:171], v184 offset:24576
	s_setprio 1
	v_mfma_f32_32x32x16_bf16 v[16:31], v[180:183], v[172:175], v[16:31]
	v_mfma_f32_32x32x16_bf16 v[0:15], v[180:183], v[176:179], v[0:15]
	s_setprio 0
	s_add_u32 m0, s80, 0x0
	s_nop 0
	global_load_lds_dwordx4 v188, s[76:77]
	s_add_u32 m0, s80, 0x3000
	s_nop 0
	global_load_lds_dwordx4 v188, s[78:79]
	s_waitcnt lgkmcnt(0)
	s_setprio 1
	v_mfma_f32_32x32x16_bf16 v[16:31], v[168:171], v[160:163], v[16:31]
	v_mfma_f32_32x32x16_bf16 v[0:15], v[168:171], v[164:167], v[0:15]
	s_setprio 0
	ds_read_b128 v[172:175], v187 offset:24576
	ds_read_b128 v[176:179], v187 offset:26624
	ds_read_b128 v[180:183], v185 offset:24576
	s_add_u32 m0, s81, 0x0
	s_nop 0
	global_load_lds_dwordx4 v189, s[76:77]
	s_add_u32 m0, s81, 0x3000
	s_nop 0
	global_load_lds_dwordx4 v189, s[78:79]
	s_add_u32 m0, s81, 0x400
	s_nop 0
	global_load_lds_dwordx4 v190, s[76:77]
	s_add_u32 m0, s81, 0x3400
	s_nop 0
	global_load_lds_dwordx4 v190, s[78:79]
	s_add_u32 s76, s76, 128
	s_addc_u32 s77, s77, 0
	s_add_u32 s78, s78, 128
	s_addc_u32 s79, s79, 0
	s_waitcnt lgkmcnt(0)
	s_barrier
	ds_read_b128 v[160:163], v186 offset:36864
	ds_read_b128 v[164:167], v186 offset:38912
	ds_read_b128 v[168:171], v184 offset:36864
	s_setprio 1
	v_mfma_f32_32x32x16_bf16 v[16:31], v[180:183], v[172:175], v[16:31]
	v_mfma_f32_32x32x16_bf16 v[0:15], v[180:183], v[176:179], v[0:15]
	s_setprio 0
	s_waitcnt lgkmcnt(0)
	s_setprio 1
	v_mfma_f32_32x32x16_bf16 v[16:31], v[168:171], v[160:163], v[16:31]
	v_mfma_f32_32x32x16_bf16 v[0:15], v[168:171], v[164:167], v[0:15]
	s_setprio 0
	ds_read_b128 v[172:175], v187 offset:36864
	ds_read_b128 v[176:179], v187 offset:38912
	ds_read_b128 v[180:183], v185 offset:36864
	s_waitcnt vmcnt(6) lgkmcnt(0)
	s_barrier
	ds_read_b128 v[160:163], v186 offset:49152
	ds_read_b128 v[164:167], v186 offset:51200
	ds_read_b128 v[168:171], v184 offset:49152
	s_setprio 1
	v_mfma_f32_32x32x16_bf16 v[16:31], v[180:183], v[172:175], v[16:31]
	v_mfma_f32_32x32x16_bf16 v[0:15], v[180:183], v[176:179], v[0:15]
	s_setprio 0
	s_add_u32 m0, s80, 0x6000
	s_nop 0
	global_load_lds_dwordx4 v188, s[76:77]
	s_add_u32 m0, s80, 0x9000
	s_nop 0
	global_load_lds_dwordx4 v188, s[78:79]
	s_waitcnt lgkmcnt(0)
	s_setprio 1
	v_mfma_f32_32x32x16_bf16 v[16:31], v[168:171], v[160:163], v[16:31]
	v_mfma_f32_32x32x16_bf16 v[0:15], v[168:171], v[164:167], v[0:15]
	s_setprio 0
	ds_read_b128 v[172:175], v187 offset:49152
	ds_read_b128 v[176:179], v187 offset:51200
	ds_read_b128 v[180:183], v185 offset:49152
	s_add_u32 m0, s81, 0x6000
	s_nop 0
	global_load_lds_dwordx4 v189, s[76:77]
	s_add_u32 m0, s81, 0x9000
	s_nop 0
	global_load_lds_dwordx4 v189, s[78:79]
	s_add_u32 m0, s81, 0x6400
	s_nop 0
	global_load_lds_dwordx4 v190, s[76:77]
	s_add_u32 m0, s81, 0x9400
	s_nop 0
	global_load_lds_dwordx4 v190, s[78:79]
	s_add_u32 s76, s76, 128
	s_addc_u32 s77, s77, 0
	s_add_u32 s78, s78, 128
	s_addc_u32 s79, s79, 0
	s_waitcnt lgkmcnt(0)
	s_barrier
	ds_read_b128 v[160:163], v186 offset:61440
	ds_read_b128 v[164:167], v186 offset:63488
	ds_read_b128 v[168:171], v184 offset:61440
	s_setprio 1
	v_mfma_f32_32x32x16_bf16 v[16:31], v[180:183], v[172:175], v[16:31]
	v_mfma_f32_32x32x16_bf16 v[0:15], v[180:183], v[176:179], v[0:15]
	s_setprio 0
	s_waitcnt lgkmcnt(0)
	s_setprio 1
	v_mfma_f32_32x32x16_bf16 v[16:31], v[168:171], v[160:163], v[16:31]
	v_mfma_f32_32x32x16_bf16 v[0:15], v[168:171], v[164:167], v[0:15]
	s_setprio 0
	ds_read_b128 v[172:175], v187 offset:61440
	ds_read_b128 v[176:179], v187 offset:63488
	ds_read_b128 v[180:183], v185 offset:61440
	s_sub_u32 s82, s82, 1
	s_cmp_lg_u32 s82, 0
	s_cbranch_scc1 .Lp5s_kloop
	s_waitcnt vmcnt(6) lgkmcnt(0)
	s_barrier
	ds_read_b128 v[160:163], v186 offset:0
	ds_read_b128 v[164:167], v186 offset:2048
	ds_read_b128 v[168:171], v184 offset:0
	s_setprio 1
	v_mfma_f32_32x32x16_bf16 v[16:31], v[180:183], v[172:175], v[16:31]
	v_mfma_f32_32x32x16_bf16 v[0:15], v[180:183], v[176:179], v[0:15]
	s_setprio 0
	s_waitcnt lgkmcnt(0)
	s_setprio 1
	v_mfma_f32_32x32x16_bf16 v[16:31], v[168:171], v[160:163], v[16:31]
	v_mfma_f32_32x32x16_bf16 v[0:15], v[168:171], v[164:167], v[0:15]
	s_setprio 0
	ds_read_b128 v[172:175], v187 offset:0
	ds_read_b128 v[176:179], v187 offset:2048
	ds_read_b128 v[180:183], v185 offset:0
	s_waitcnt lgkmcnt(0)
	s_barrier
	ds_read_b128 v[160:163], v186 offset:12288
	ds_read_b128 v[164:167], v186 offset:14336
	ds_read_b128 v[168:171], v184 offset:12288
	s_setprio 1
	v_mfma_f32_32x32x16_bf16 v[16:31], v[180:183], v[172:175], v[16:31]
	v_mfma_f32_32x32x16_bf16 v[0:15], v[180:183], v[176:179], v[0:15]
	s_setprio 0
	s_waitcnt lgkmcnt(0)
	s_setprio 1
	v_mfma_f32_32x32x16_bf16 v[16:31], v[168:171], v[160:163], v[16:31]
	v_mfma_f32_32x32x16_bf16 v[0:15], v[168:171], v[164:167], v[0:15]
	s_setprio 0
	ds_read_b128 v[172:175], v187 offset:12288
	ds_read_b128 v[176:179], v187 offset:14336
	ds_read_b128 v[180:183], v185 offset:12288
	s_waitcnt vmcnt(0) lgkmcnt(0)
	s_barrier
	ds_read_b128 v[160:163], v186 offset:24576
	ds_read_b128 v[164:167], v186 offset:26624
	ds_read_b128 v[168:171], v184 offset:24576
	s_setprio 1
	v_mfma_f32_32x32x16_bf16 v[16:31], v[180:183], v[172:175], v[16:31]
	v_mfma_f32_32x32x16_bf16 v[0:15], v[180:183], v[176:179], v[0:15]
	s_setprio 0
	s_waitcnt lgkmcnt(0)
	s_setprio 1
	v_mfma_f32_32x32x16_bf16 v[16:31], v[168:171], v[160:163], v[16:31]
	v_mfma_f32_32x32x16_bf16 v[0:15], v[168:171], v[164:167], v[0:15]
	s_setprio 0
	ds_read_b128 v[172:175], v187 offset:24576
	ds_read_b128 v[176:179], v187 offset:26624
	ds_read_b128 v[180:183], v185 offset:24576
	s_waitcnt lgkmcnt(0)
	s_barrier
	ds_read_b128 v[160:163], v186 offset:36864
	ds_read_b128 v[164:167], v186 offset:38912
	ds_read_b128 v[168:171], v184 offset:36864
	s_setprio 1
	v_mfma_f32_32x32x16_bf16 v[16:31], v[180:183], v[172:175], v[16:31]
	v_mfma_f32_32x32x16_bf16 v[0:15], v[180:183], v[176:179], v[0:15]
	s_setprio 0
	s_waitcnt lgkmcnt(0)
	s_setprio 1
	v_mfma_f32_32x32x16_bf16 v[16:31], v[168:171], v[160:163], v[16:31]
	v_mfma_f32_32x32x16_bf16 v[0:15], v[168:171], v[164:167], v[0:15]
	s_setprio 0
	ds_read_b128 v[172:175], v187 offset:36864
	ds_read_b128 v[176:179], v187 offset:38912
	ds_read_b128 v[180:183], v185 offset:36864
	s_waitcnt lgkmcnt(0)
	s_setprio 1
	v_mfma_f32_32x32x16_bf16 v[16:31], v[180:183], v[172:175], v[16:31]
	v_mfma_f32_32x32x16_bf16 v[0:15], v[180:183], v[176:179], v[0:15]
	s_setprio 0
	s_branch .LBB0_713
